# v15 = v14 + K2 tile DMA moved into the prefetched load group (issued right after K1)
# baseline (speedup 1.0000x reference)
.Lnbp_556:
	s_or_b64 exec, exec, s[60:61]
	s_add_u32 s98, s64, 0x48000
	s_addc_u32 s99, s65, 0
	s_add_i32 m0, s73, 0x6000
	s_nop 0
	global_load_lds_dwordx4 v183, s[98:99]
	s_and_saveexec_b64 s[100:101], s[2:3]
	s_add_u32 s98, s46, 0x2000
	s_addc_u32 s99, s47, 0
	s_add_i32 m0, s76, 0x6000
	s_nop 0
	global_load_lds_dwordx4 v184, s[98:99]
	s_or_b64 exec, exec, s[100:101]
	s_lshl_b64 s[60:61], s[56:57], 18
	v_readlane_b32 s1, v246, 39
	s_add_u32 s1, s1, s44
	v_readlane_b32 s44, v246, 40
	s_addc_u32 s44, s44, s45
	s_add_u32 s1, s1, s48
	s_addc_u32 s48, s44, s49
	s_lshl_b64 s[44:45], s[60:61], 2
	v_readlane_b32 s49, v246, 51
	s_add_u32 s44, s49, s44
	v_readlane_b32 s49, v246, 52
	s_addc_u32 s45, s49, s45
	s_lshl_b32 s81, s62, 8
	s_add_i32 s52, s81, s71
	v_or_b32_e32 v76, s52, v170
	v_mov_b32_e32 v77, v153
	v_lshlrev_b64 v[76:77], 7, v[76:77]
	v_lshl_add_u64 v[76:77], s[44:45], 0, v[76:77]
	v_lshl_add_u64 v[72:73], v[146:147], 2, v[76:77]
	s_mul_i32 s44, s52, 0x900
	s_mov_b32 s98, s0
	s_ashr_i32 s99, s0, 31
	s_lshl_b64 s[98:99], s[98:99], 9
	s_lshl_b32 s100, s56, 7
	s_ashr_i32 s101, s100, 31
	v_lshl_add_u64 v[250:251], v[162:163], 0, s[98:99]
	v_lshl_add_u64 v[252:253], s[100:101], 2, v[164:165]
	global_load_dword v247, v[250:251], off
	global_load_dword v248, v[250:251], off offset:256
	global_load_dword v249, v[252:253], off
	global_load_dword v254, v[252:253], off offset:256
	global_load_dwordx4 v[48:51], v[72:73], off
	global_load_dwordx4 v[52:55], v[72:73], off offset:16
	s_mul_hi_u32 s45, s52, 0x900
	global_load_dwordx4 v[56:59], v[72:73], off offset:48
	s_nop 0
	global_load_dwordx4 v[60:63], v[72:73], off offset:32
	s_add_u32 s44, s1, s44
	s_addc_u32 s45, s48, s45
	v_lshl_add_u64 v[78:79], s[44:45], 0, v[152:153]
	v_lshl_add_u64 v[74:75], v[150:151], 1, v[78:79]
	global_load_dwordx4 v[64:67], v[74:75], off offset:128
	global_load_dwordx4 v[68:71], v[74:75], off offset:160
	global_load_dwordx4 v[116:119], v[74:75], off
	global_load_dwordx4 v[112:115], v[74:75], off offset:32
	global_load_dwordx4 v[104:107], v[74:75], off offset:64
	global_load_dwordx4 v[96:99], v[74:75], off offset:96

.LBB0_556:
	s_or_b64 exec, exec, s[60:61]
	s_add_u32 s98, s64, 0x48000
	s_addc_u32 s99, s65, 0
	s_add_i32 m0, s73, 0x6000
	s_nop 0
	global_load_lds_dwordx4 v183, s[98:99]
	s_and_saveexec_b64 s[100:101], s[2:3]
	s_add_u32 s98, s46, 0x2000
	s_addc_u32 s99, s47, 0
	s_add_i32 m0, s76, 0x6000
	s_nop 0
	global_load_lds_dwordx4 v184, s[98:99]
	s_or_b64 exec, exec, s[100:101]
	s_lshl_b64 s[60:61], s[56:57], 18
	v_readlane_b32 s1, v246, 39
	s_add_u32 s1, s1, s44
	v_readlane_b32 s44, v246, 40
	s_addc_u32 s44, s44, s45
	s_add_u32 s1, s1, s48
	s_addc_u32 s48, s44, s49
	s_lshl_b64 s[44:45], s[60:61], 2
	v_readlane_b32 s49, v246, 51
	s_add_u32 s44, s49, s44
	v_readlane_b32 s49, v246, 52
	s_addc_u32 s45, s49, s45
	s_lshl_b32 s81, s62, 8
	s_add_i32 s52, s81, s71
	v_or_b32_e32 v0, s52, v170
	v_mov_b32_e32 v1, v153
	v_lshlrev_b64 v[0:1], 7, v[0:1]
	v_lshl_add_u64 v[0:1], s[44:45], 0, v[0:1]
	v_lshl_add_u64 v[12:13], v[146:147], 2, v[0:1]
	s_mul_i32 s44, s52, 0x900
	s_mov_b32 s98, s0
	s_ashr_i32 s99, s0, 31
	s_lshl_b64 s[98:99], s[98:99], 9
	s_lshl_b32 s100, s56, 7
	s_ashr_i32 s101, s100, 31
	v_lshl_add_u64 v[250:251], v[162:163], 0, s[98:99]
	v_lshl_add_u64 v[252:253], s[100:101], 2, v[164:165]
	global_load_dword v247, v[250:251], off
	global_load_dword v248, v[250:251], off offset:256
	global_load_dword v249, v[252:253], off
	global_load_dword v254, v[252:253], off offset:256
	global_load_dwordx4 v[0:3], v[12:13], off
	global_load_dwordx4 v[4:7], v[12:13], off offset:16
	s_mul_hi_u32 s45, s52, 0x900
	global_load_dwordx4 v[8:11], v[12:13], off offset:48
	s_nop 0
	global_load_dwordx4 v[12:15], v[12:13], off offset:32
	s_add_u32 s44, s1, s44
	s_addc_u32 s45, s48, s45
	v_lshl_add_u64 v[16:17], s[44:45], 0, v[152:153]
	v_lshl_add_u64 v[24:25], v[150:151], 1, v[16:17]
	global_load_dwordx4 v[16:19], v[24:25], off offset:128
	global_load_dwordx4 v[20:23], v[24:25], off offset:160
	global_load_dwordx4 v[116:119], v[24:25], off
	global_load_dwordx4 v[112:115], v[24:25], off offset:32
	global_load_dwordx4 v[104:107], v[24:25], off offset:64
	global_load_dwordx4 v[96:99], v[24:25], off offset:96

.LBB0_559:
.LBB0_561:
	s_waitcnt vmcnt(5) lgkmcnt(0)
	s_barrier
	ds_read_b128 v[36:39], v179
	ds_read_b128 v[40:43], v179 offset:512
	ds_read_b128 v[44:47], v179 offset:2048
	ds_read_b128 v[48:51], v179 offset:2560
	ds_read_b128 v[52:55], v179 offset:4096
	ds_read_b128 v[56:59], v179 offset:4608
	ds_read_b128 v[60:63], v179 offset:6144
	ds_read_b128 v[64:67], v179 offset:6656
	ds_read_b128 v[68:71], v179 offset:8192
	ds_read_b128 v[72:75], v179 offset:8704
	ds_read_b128 v[76:79], v179 offset:10240
	ds_read_b128 v[80:83], v179 offset:10752
	s_cmp_lg_u32 s62, 0
	s_cselect_b64 s[0:1], -1, 0
	s_and_b64 vcc, exec, s[0:1]
	s_waitcnt lgkmcnt(11)
	v_mfma_f32_32x32x16_bf16 v[16:31], v[36:39], v[116:119], 0
	s_waitcnt lgkmcnt(10)
	v_mfma_f32_32x32x16_bf16 v[0:15], v[40:43], v[116:119], 0
	s_waitcnt lgkmcnt(9)
	v_mfma_f32_32x32x16_bf16 v[16:31], v[44:47], v[112:115], v[16:31]
	s_waitcnt lgkmcnt(8)
	v_mfma_f32_32x32x16_bf16 v[0:15], v[48:51], v[112:115], v[0:15]
	s_waitcnt lgkmcnt(7)
	v_mfma_f32_32x32x16_bf16 v[16:31], v[52:55], v[104:107], v[16:31]
	s_waitcnt lgkmcnt(6)
	v_mfma_f32_32x32x16_bf16 v[0:15], v[56:59], v[104:107], v[0:15]
	s_waitcnt lgkmcnt(5)
	v_mfma_f32_32x32x16_bf16 v[16:31], v[60:63], v[96:99], v[16:31]
	s_waitcnt lgkmcnt(4)
	v_mfma_f32_32x32x16_bf16 v[0:15], v[64:67], v[96:99], v[0:15]
	s_waitcnt lgkmcnt(3)
	v_mfma_f32_32x32x16_bf16 v[16:31], v[68:71], v[108:111], v[16:31]
	s_waitcnt lgkmcnt(2)
	v_mfma_f32_32x32x16_bf16 v[0:15], v[72:75], v[108:111], v[0:15]
	s_waitcnt lgkmcnt(1)
	v_mfma_f32_32x32x16_bf16 v[16:31], v[76:79], v[100:103], v[16:31]
	s_waitcnt lgkmcnt(0)
	v_mfma_f32_32x32x16_bf16 v[0:15], v[80:83], v[100:103], v[0:15]
	s_cbranch_vccnz .LBB0_563
	v_readlane_b32 s48, v246, 61
	v_readlane_b32 s49, v246, 62
	s_nop 5
	v_cndmask_b32_e64 v32, v16, v218, s[48:49]
	v_readlane_b32 s48, v246, 63
	v_readlane_b32 s49, v245, 0
	s_nop 1
	v_cndmask_b32_e64 v0, v0, v218, s[48:49]
	v_readlane_b32 s48, v245, 1
	v_readlane_b32 s49, v245, 2
	s_nop 1
	v_cndmask_b32_e64 v17, v218, v17, s[48:49]
	v_cndmask_b32_e64 v16, v32, v16, s[48:49]
	v_readlane_b32 s48, v245, 3
	v_readlane_b32 s49, v245, 4
	s_nop 1
	v_cndmask_b32_e64 v1, v1, v218, s[48:49]
	v_readlane_b32 s48, v245, 5
	v_readlane_b32 s49, v245, 6
	s_nop 1
	v_cndmask_b32_e64 v18, v18, v218, s[48:49]
	v_readlane_b32 s48, v245, 7
	v_readlane_b32 s49, v245, 8
	s_nop 1
	v_cndmask_b32_e64 v2, v2, v218, s[48:49]
	v_readlane_b32 s48, v245, 9
	v_readlane_b32 s49, v245, 10
	s_nop 1
	v_cndmask_b32_e64 v19, v19, v218, s[48:49]
	v_readlane_b32 s48, v245, 11
	v_readlane_b32 s49, v245, 12
	s_nop 1
	v_cndmask_b32_e64 v3, v3, v218, s[48:49]
	v_readlane_b32 s48, v245, 13
	v_readlane_b32 s49, v245, 14
	s_nop 1
	v_cndmask_b32_e64 v20, v20, v218, s[48:49]
	v_readlane_b32 s48, v245, 15
	v_readlane_b32 s49, v245, 16
	s_nop 1
	v_cndmask_b32_e64 v4, v4, v218, s[48:49]
	v_readlane_b32 s48, v245, 17
	v_readlane_b32 s49, v245, 18
	s_nop 1
	v_cndmask_b32_e64 v21, v21, v218, s[48:49]
	v_readlane_b32 s48, v245, 19
	v_readlane_b32 s49, v245, 20
	s_nop 1
	v_cndmask_b32_e64 v5, v5, v218, s[48:49]
	v_readlane_b32 s48, v245, 21
	v_readlane_b32 s49, v245, 22
	s_nop 1
	v_cndmask_b32_e64 v22, v22, v218, s[48:49]
	v_readlane_b32 s48, v245, 23
	v_readlane_b32 s49, v245, 24
	s_nop 1
	v_cndmask_b32_e64 v6, v6, v218, s[48:49]
	v_readlane_b32 s48, v245, 25
	v_readlane_b32 s49, v245, 26
	s_nop 1
	v_cndmask_b32_e64 v23, v23, v218, s[48:49]
	v_readlane_b32 s48, v245, 27
	v_readlane_b32 s49, v245, 28
	s_nop 1
	v_cndmask_b32_e64 v7, v7, v218, s[48:49]
	v_readlane_b32 s48, v245, 29
	v_readlane_b32 s49, v245, 30
	s_nop 1
	v_cndmask_b32_e64 v24, v24, v218, s[48:49]
	v_readlane_b32 s48, v245, 31
	v_readlane_b32 s49, v245, 32
	s_nop 1
	v_cndmask_b32_e64 v8, v8, v218, s[48:49]
	v_readlane_b32 s48, v245, 33
	v_readlane_b32 s49, v245, 34
	s_nop 1
	v_cndmask_b32_e64 v25, v25, v218, s[48:49]
	v_readlane_b32 s48, v245, 35
	v_readlane_b32 s49, v245, 36
	s_nop 1
	v_cndmask_b32_e64 v9, v9, v218, s[48:49]
	v_readlane_b32 s48, v245, 37
	v_readlane_b32 s49, v245, 38
	s_nop 1
	v_cndmask_b32_e64 v26, v26, v218, s[48:49]
	v_readlane_b32 s48, v245, 39
	v_readlane_b32 s49, v245, 40
	s_nop 1
	v_cndmask_b32_e64 v10, v10, v218, s[48:49]
	v_readlane_b32 s48, v245, 41
	v_readlane_b32 s49, v245, 42
	s_nop 1
	v_cndmask_b32_e64 v27, v27, v218, s[48:49]
	v_readlane_b32 s48, v245, 43
	v_readlane_b32 s49, v245, 44
	s_nop 1
	v_cndmask_b32_e64 v11, v11, v218, s[48:49]
	v_readlane_b32 s48, v245, 45
	v_readlane_b32 s49, v245, 46
	s_nop 1
	v_cndmask_b32_e64 v28, v28, v218, s[48:49]
	v_readlane_b32 s48, v245, 47
	v_readlane_b32 s49, v245, 48
	s_nop 1
	v_cndmask_b32_e64 v12, v12, v218, s[48:49]
	v_readlane_b32 s48, v245, 49
	v_readlane_b32 s49, v245, 50
	s_nop 1
	v_cndmask_b32_e64 v29, v29, v218, s[48:49]
	v_readlane_b32 s48, v245, 51
	v_readlane_b32 s49, v245, 52
	s_nop 1
	v_cndmask_b32_e64 v13, v13, v218, s[48:49]
	v_readlane_b32 s48, v245, 53
	v_readlane_b32 s49, v245, 54
	s_nop 1
	v_cndmask_b32_e64 v30, v30, v218, s[48:49]
	v_readlane_b32 s48, v245, 55
	v_readlane_b32 s49, v245, 56
	s_nop 1
	v_cndmask_b32_e64 v14, v14, v218, s[48:49]
	v_readlane_b32 s48, v245, 57
	v_readlane_b32 s49, v245, 58
	s_nop 1
	v_cndmask_b32_e64 v31, v31, v218, s[48:49]
	v_readlane_b32 s48, v245, 59
	v_readlane_b32 s49, v245, 60
	s_nop 1
	v_cndmask_b32_e64 v15, v15, v218, s[48:49]
